# s_setprio 3 on the wave that runs N, E1, E2/E3 (the block's serial section), back to 0 before the barrier
# speedup vs baseline: 1.0338x; 1.0056x over previous
.Ld_w0_a:
	s_setprio 3
	v_mul_u32_u24_e32 v89, 0x84, v112
	v_lshl_add_u32 v89, v98, 2, v89
	v_add_u32_e32 v89, 0x2080, v89
	v_cmp_lt_u32_e32 vcc, v112, v98
	v_cmp_lt_u32_e64 s[10:11], v112, v213
	v_cmp_lt_u32_e64 s[36:37], v112, v214
	v_cndmask_b32_e64 v32, 0, v32, vcc
	v_cmp_lt_u32_e32 vcc, v112, v215
	v_cndmask_b32_e64 v33, 0, v33, s[10:11]
	v_cmp_lt_u32_e64 s[10:11], v112, v216
	ds_write2_b32 v89, v32, v33 offset0:0 offset1:1
	v_cndmask_b32_e64 v34, 0, v34, s[36:37]
	v_cmp_lt_u32_e64 s[36:37], v112, v217
	v_cndmask_b32_e64 v35, 0, v35, vcc
	v_cmp_lt_u32_e32 vcc, v112, v218
	ds_write2_b32 v89, v34, v35 offset0:2 offset1:3
	v_cndmask_b32_e64 v36, 0, v36, s[10:11]
	v_cmp_lt_u32_e64 s[10:11], v112, v219
	v_cndmask_b32_e64 v37, 0, v37, s[36:37]
	v_cmp_lt_u32_e64 s[36:37], v112, v220
	ds_write2_b32 v89, v36, v37 offset0:8 offset1:9
	v_cndmask_b32_e64 v38, 0, v38, vcc
	v_cmp_lt_u32_e32 vcc, v112, v221
	v_cndmask_b32_e64 v39, 0, v39, s[10:11]
	v_cmp_lt_u32_e64 s[10:11], v112, v222
	ds_write2_b32 v89, v38, v39 offset0:10 offset1:11
	v_cndmask_b32_e64 v40, 0, v40, s[36:37]
	v_cmp_lt_u32_e64 s[36:37], v112, v223
	v_cndmask_b32_e64 v41, 0, v41, vcc
	v_cmp_lt_u32_e32 vcc, v112, v224
	ds_write2_b32 v89, v40, v41 offset0:16 offset1:17
	v_cndmask_b32_e64 v42, 0, v42, s[10:11]
	v_cmp_lt_u32_e64 s[10:11], v112, v225
	v_cndmask_b32_e64 v43, 0, v43, s[36:37]
	v_cmp_lt_u32_e64 s[36:37], v112, v226
	ds_write2_b32 v89, v42, v43 offset0:18 offset1:19
	v_cndmask_b32_e64 v44, 0, v44, vcc
	v_cmp_lt_u32_e32 vcc, v112, v227
	v_cndmask_b32_e64 v45, 0, v45, s[10:11]
	ds_write2_b32 v89, v44, v45 offset0:24 offset1:25
	v_cndmask_b32_e64 v46, 0, v46, s[36:37]
	v_cndmask_b32_e64 v47, 0, v47, vcc
	ds_write2_b32 v89, v46, v47 offset0:26 offset1:27

.LBB0_1034:
	s_or_b64 exec, exec, s[36:37]
	s_cmp_lg_u64 s[30:31], 0
	s_cbranch_scc1 .Le23_skip_a
	v_and_b32_e32 v33, 15, v113
	v_lshrrev_b32_e32 v35, 4, v113
	v_mul_u32_u24_e32 v36, 0x84, v35
	v_mul_u32_u24_e32 v37, 0x44, v33
	v_mul_u32_u24_e32 v38, 0x110, v35
	v_lshl_add_u32 v36, v33, 2, v36
	v_lshl_add_u32 v37, v35, 2, v37
	v_lshl_add_u32 v38, v33, 2, v38
	ds_read_b32 v40, v36 offset:8384
	ds_read_b32 v44, v37 offset:12544
	ds_read_b32 v41, v36 offset:8912
	ds_read_b32 v45, v37 offset:12560
	ds_read_b32 v42, v36 offset:9440
	ds_read_b32 v46, v37 offset:12576
	ds_read_b32 v43, v36 offset:9968
	ds_read_b32 v47, v37 offset:12592
	ds_read_b32 v214, v38 offset:13632
	ds_read_b32 v215, v38 offset:13700
	ds_read_b32 v216, v38 offset:13768
	ds_read_b32 v217, v38 offset:13836
	v_mul_u32_u24_e32 v88, 0x50, v33
	v_lshl_add_u32 v88, v35, 3, v88
	v_lshrrev_b32_e32 v39, 2, v113
	v_mul_u32_u24_e32 v39, 0x50, v39
	v_and_b32_e32 v33, 3, v113
	v_lshl_add_u32 v39, v33, 3, v39
	v_mov_b32_e32 v230, 0
	v_mov_b32_e32 v231, 0
	ds_write_b64 v39, v[230:231] offset:58336
	s_waitcnt lgkmcnt(11)
	v_mfma_f32_16x16x4_f32 v[220:223], v40, v44, 0
	s_waitcnt lgkmcnt(9)
	v_mfma_f32_16x16x4_f32 v[220:223], v41, v45, v[220:223]
	s_waitcnt lgkmcnt(7)
	v_mfma_f32_16x16x4_f32 v[220:223], v42, v46, v[220:223]
	s_waitcnt lgkmcnt(5)
	v_mfma_f32_16x16x4_f32 v[220:223], v43, v47, v[220:223]
	s_waitcnt lgkmcnt(1)
	s_nop 9
	v_mfma_f32_16x16x4_f32 v[224:227], v220, v214, 0
	v_mfma_f32_16x16x4_f32 v[224:227], v221, v215, v[224:227]
	v_mfma_f32_16x16x4_f32 v[224:227], v222, v216, v[224:227]
	v_mfma_f32_16x16x4_f32 v[224:227], v223, v217, v[224:227]
	s_nop 9
	v_cvt_pk_bf16_f32 v228, v224, v225
	v_cvt_pk_bf16_f32 v229, v226, v227
	ds_write_b64 v88, v[228:229] offset:59584
	s_setprio 0

.Ld_w0_b:
	s_setprio 3
	v_mul_u32_u24_e32 v52, 0x84, v70
	v_lshl_add_u32 v52, v0, 2, v52
	v_add_u32_e32 v52, 0x2080, v52
	v_cmp_lt_u32_e32 vcc, v70, v0
	v_cmp_lt_u32_e64 s[12:13], v70, v143
	v_cmp_lt_u32_e64 s[58:59], v70, v158
	v_cndmask_b32_e64 v34, 0, v34, vcc
	v_cmp_lt_u32_e32 vcc, v70, v159
	v_cndmask_b32_e64 v35, 0, v35, s[12:13]
	v_cmp_lt_u32_e64 s[12:13], v70, v160
	ds_write2_b32 v52, v34, v35 offset0:0 offset1:1
	v_cndmask_b32_e64 v36, 0, v36, s[58:59]
	v_cmp_lt_u32_e64 s[58:59], v70, v161
	v_cndmask_b32_e64 v37, 0, v37, vcc
	v_cmp_lt_u32_e32 vcc, v70, v162
	ds_write2_b32 v52, v36, v37 offset0:2 offset1:3
	v_cndmask_b32_e64 v38, 0, v38, s[12:13]
	v_cmp_lt_u32_e64 s[12:13], v70, v163
	v_cndmask_b32_e64 v39, 0, v39, s[58:59]
	v_cmp_lt_u32_e64 s[58:59], v70, v164
	ds_write2_b32 v52, v38, v39 offset0:8 offset1:9
	v_cndmask_b32_e64 v40, 0, v40, vcc
	v_cmp_lt_u32_e32 vcc, v70, v165
	v_cndmask_b32_e64 v41, 0, v41, s[12:13]
	v_cmp_lt_u32_e64 s[12:13], v70, v166
	ds_write2_b32 v52, v40, v41 offset0:10 offset1:11
	v_cndmask_b32_e64 v42, 0, v42, s[58:59]
	v_cmp_lt_u32_e64 s[58:59], v70, v167
	v_cndmask_b32_e64 v43, 0, v43, vcc
	v_cmp_lt_u32_e32 vcc, v70, v168
	ds_write2_b32 v52, v42, v43 offset0:16 offset1:17
	v_cndmask_b32_e64 v44, 0, v44, s[12:13]
	v_cmp_lt_u32_e64 s[12:13], v70, v169
	v_cndmask_b32_e64 v45, 0, v45, s[58:59]
	v_cmp_lt_u32_e64 s[58:59], v70, v170
	ds_write2_b32 v52, v44, v45 offset0:18 offset1:19
	v_cndmask_b32_e64 v46, 0, v46, vcc
	v_cmp_lt_u32_e32 vcc, v70, v171
	v_cndmask_b32_e64 v47, 0, v47, s[12:13]
	ds_write2_b32 v52, v46, v47 offset0:24 offset1:25
	v_cndmask_b32_e64 v48, 0, v48, s[58:59]
	v_cndmask_b32_e64 v49, 0, v49, vcc
	ds_write2_b32 v52, v48, v49 offset0:26 offset1:27

.LBB0_1213:
	s_or_b64 exec, exec, s[58:59]
	s_cmp_lg_u64 s[54:55], 0
	s_cbranch_scc1 .Le23_skip_b
	v_and_b32_e32 v34, 15, v141
	v_bfe_u32 v35, v141, 4, 2
	v_mul_u32_u24_e32 v36, 0x84, v35
	v_mul_u32_u24_e32 v37, 0x44, v34
	v_mul_u32_u24_e32 v38, 0x110, v35
	v_lshl_add_u32 v36, v34, 2, v36
	v_lshl_add_u32 v37, v35, 2, v37
	v_lshl_add_u32 v38, v34, 2, v38
	ds_read_b32 v40, v36 offset:8384
	ds_read_b32 v44, v37 offset:12544
	ds_read_b32 v41, v36 offset:8912
	ds_read_b32 v45, v37 offset:12560
	ds_read_b32 v42, v36 offset:9440
	ds_read_b32 v46, v37 offset:12576
	ds_read_b32 v43, v36 offset:9968
	ds_read_b32 v47, v37 offset:12592
	ds_read_b32 v214, v38 offset:13632
	ds_read_b32 v215, v38 offset:13700
	ds_read_b32 v216, v38 offset:13768
	ds_read_b32 v217, v38 offset:13836
	v_mul_u32_u24_e32 v48, 0x50, v34
	v_lshl_add_u32 v48, v35, 3, v48
	v_bfe_u32 v39, v141, 2, 4
	v_mul_u32_u24_e32 v39, 0x50, v39
	v_and_b32_e32 v34, 3, v141
	v_lshl_add_u32 v39, v34, 3, v39
	v_mov_b32_e32 v230, 0
	v_mov_b32_e32 v231, 0
	ds_write_b64 v39, v[230:231] offset:58336
	s_waitcnt lgkmcnt(11)
	v_mfma_f32_16x16x4_f32 v[220:223], v40, v44, 0
	s_waitcnt lgkmcnt(9)
	v_mfma_f32_16x16x4_f32 v[220:223], v41, v45, v[220:223]
	s_waitcnt lgkmcnt(7)
	v_mfma_f32_16x16x4_f32 v[220:223], v42, v46, v[220:223]
	s_waitcnt lgkmcnt(5)
	v_mfma_f32_16x16x4_f32 v[220:223], v43, v47, v[220:223]
	s_waitcnt lgkmcnt(1)
	s_nop 9
	v_mfma_f32_16x16x4_f32 v[224:227], v220, v214, 0
	v_mfma_f32_16x16x4_f32 v[224:227], v221, v215, v[224:227]
	v_mfma_f32_16x16x4_f32 v[224:227], v222, v216, v[224:227]
	v_mfma_f32_16x16x4_f32 v[224:227], v223, v217, v[224:227]
	s_nop 9
	v_cvt_pk_bf16_f32 v228, v224, v225
	v_cvt_pk_bf16_f32 v229, v226, v227
	ds_write_b64 v48, v[228:229] offset:59584
	s_setprio 0
